# P3 stage A: prefetch 8 token rows per wave by LDS-DMA instead of 8 serialized load round trips
# baseline (speedup 1.0000x reference)
.LBB0_421:
	s_and_b64 vcc, exec, s[16:17]
	s_cbranch_vccz .LBB0_394
	s_ashr_i32 s60, s58, 10
	s_and_b32 s56, s58, 0x7f
	s_bfe_u32 s59, s58, 0x30007
	s_ashr_i32 s61, s60, 31
	s_lshl_b32 s9, s56, 6
	s_lshl_b64 s[62:63], s[60:61], 13
	s_lshl_b32 s44, s59, 12
	s_add_u32 s16, s22, s44
	s_addc_u32 s17, s23, 0
	v_mov_b32_e32 v141, v43
	v_lshl_add_u64 v[4:5], s[16:17], 0, v[140:141]
	s_mov_b64 s[16:17], 0x8000
	v_mov_b32_e32 v240, 0
	v_lshl_add_u64 v[2:3], v[110:111], 0, s[44:45]
	v_lshl_add_u64 v[14:15], v[4:5], 0, s[16:17]
	s_mov_b32 s16, 0x8000
	s_or_b32 s66, s62, s9
	s_add_u32 s66, s66, s84
	s_addc_u32 s67, s63, 0
	s_lshl_b64 s[66:67], s[66:67], 11
	v_lshl_add_u64 v[162:163], v[112:113], 0, s[66:67]
	s_lshl_b32 s68, s36, 14
	s_cmp_ge_u32 s36, 6
	s_cselect_b32 s69, 0x800, 0
	s_add_u32 s68, s68, s69
	v_lshl_add_u32 v164, v146, 4, s68
	s_mov_b64 s[70:71], 0x400
	s_mov_b32 m0, s68
	s_add_u32 s68, s68, 0x400
	global_load_lds_dwordx4 v[162:163], off
	v_lshl_add_u64 v[162:163], v[162:163], 0, s[70:71]
	s_mov_b32 m0, s68
	s_add_u32 s68, s68, 0x400
	global_load_lds_dwordx4 v[162:163], off
	v_lshl_add_u64 v[162:163], v[162:163], 0, s[70:71]
	s_mov_b32 m0, s68
	s_add_u32 s68, s68, 0x400
	global_load_lds_dwordx4 v[162:163], off
	v_lshl_add_u64 v[162:163], v[162:163], 0, s[70:71]
	s_mov_b32 m0, s68
	s_add_u32 s68, s68, 0x400
	global_load_lds_dwordx4 v[162:163], off
	v_lshl_add_u64 v[162:163], v[162:163], 0, s[70:71]
	s_mov_b32 m0, s68
	s_add_u32 s68, s68, 0x400
	global_load_lds_dwordx4 v[162:163], off
	v_lshl_add_u64 v[162:163], v[162:163], 0, s[70:71]
	s_mov_b32 m0, s68
	s_add_u32 s68, s68, 0x400
	global_load_lds_dwordx4 v[162:163], off
	v_lshl_add_u64 v[162:163], v[162:163], 0, s[70:71]
	s_mov_b32 m0, s68
	s_add_u32 s68, s68, 0x400
	global_load_lds_dwordx4 v[162:163], off
	v_lshl_add_u64 v[162:163], v[162:163], 0, s[70:71]
	s_mov_b32 m0, s68
	s_add_u32 s68, s68, 0x400
	global_load_lds_dwordx4 v[162:163], off
	v_lshl_add_u64 v[162:163], v[162:163], 0, s[70:71]
	s_mov_b32 m0, s68
	s_add_u32 s68, s68, 0x400
	global_load_lds_dwordx4 v[162:163], off
	v_lshl_add_u64 v[162:163], v[162:163], 0, s[70:71]
	s_mov_b32 m0, s68
	s_add_u32 s68, s68, 0x400
	global_load_lds_dwordx4 v[162:163], off
	v_lshl_add_u64 v[162:163], v[162:163], 0, s[70:71]
	s_mov_b32 m0, s68
	s_add_u32 s68, s68, 0x400
	global_load_lds_dwordx4 v[162:163], off
	v_lshl_add_u64 v[162:163], v[162:163], 0, s[70:71]
	s_mov_b32 m0, s68
	s_add_u32 s68, s68, 0x400
	global_load_lds_dwordx4 v[162:163], off
	v_lshl_add_u64 v[162:163], v[162:163], 0, s[70:71]
	s_mov_b32 m0, s68
	s_add_u32 s68, s68, 0x400
	global_load_lds_dwordx4 v[162:163], off
	v_lshl_add_u64 v[162:163], v[162:163], 0, s[70:71]
	s_mov_b32 m0, s68
	s_add_u32 s68, s68, 0x400
	global_load_lds_dwordx4 v[162:163], off
	v_lshl_add_u64 v[162:163], v[162:163], 0, s[70:71]
	s_mov_b32 m0, s68
	s_add_u32 s68, s68, 0x400
	global_load_lds_dwordx4 v[162:163], off
	v_lshl_add_u64 v[162:163], v[162:163], 0, s[70:71]
	s_mov_b32 m0, s68
	s_add_u32 s68, s68, 0x400
	global_load_lds_dwordx4 v[162:163], off
	global_load_dwordx4 v[18:21], v[2:3], off offset:16
	global_load_dwordx4 v[26:29], v[2:3], off
	global_load_dwordx4 v[6:9], v[2:3], off offset:2064
	global_load_dwordx4 v[10:13], v[2:3], off offset:2048
	v_add_co_u32_e32 v2, vcc, s16, v4
	s_mov_b64 s[16:17], s[0:1]
	s_nop 0
	v_addc_co_u32_e32 v3, vcc, 0, v5, vcc
	global_load_dwordx4 v[30:33], v[2:3], off
	global_load_dwordx4 v[22:25], v[14:15], off offset:16
	s_nop 0
	global_load_dwordx4 v[2:5], v[14:15], off offset:2064
	s_nop 0
	global_load_dwordx4 v[14:17], v[14:15], off offset:2048
	s_load_dwordx2 s[16:17], s[16:17], 0x50
	s_lshl_b32 s44, s59, 2
	v_mov_b32_e32 v34, s44
	s_or_b32 s44, s62, s9
	v_add_u32_e32 v241, 0x18000, v240
	s_waitcnt lgkmcnt(0)
	global_load_dword v35, v34, s[16:17]
	s_mov_b64 s[16:17], s[0:1]
	s_load_dwordx2 s[16:17], s[16:17], 0x58
	s_mov_b32 s61, s63
	s_waitcnt lgkmcnt(0)
	global_load_dword v141, v34, s[16:17]
	s_add_u32 s16, s44, s84
	s_addc_u32 s17, s63, 0
	s_lshl_b64 s[16:17], s[16:17], 11
	s_waitcnt vmcnt(0)
	v_mul_f32_e32 v36, 0x3fb8aa3b, v35
	v_fma_f32 v37, v35, s5, -v36
	v_rndne_f32_e32 v42, v36
	v_fmac_f32_e32 v37, 0x32a5705f, v35
	v_sub_f32_e32 v36, v36, v42
	v_add_f32_e32 v36, v36, v37
	v_exp_f32_e32 v36, v36
	v_cvt_i32_f32_e32 v37, v42
	v_cmp_ngt_f32_e32 vcc, s6, v35
	v_ldexp_f32 v36, v36, v37
	s_nop 0
	v_cndmask_b32_e32 v36, 0, v36, vcc
	v_cmp_nlt_f32_e32 vcc, s7, v35
	v_lshl_add_u64 v[34:35], v[112:113], 0, s[16:17]
	s_nop 0
	v_cndmask_b32_e32 v42, v235, v36, vcc
	ds_read_b128 v[142:145], v164 offset:0
	s_nop 0
	ds_read_b128 v[34:37], v164 offset:1024
	s_waitcnt lgkmcnt(1)
	v_lshlrev_b32_e32 v157, 16, v142
	v_and_b32_e32 v142, 0xffff0000, v142
	v_mul_f32_e32 v158, v27, v142
	v_mul_f32_e32 v142, v31, v142
	v_fmac_f32_e32 v158, v26, v157
	v_fmac_f32_e32 v142, v30, v157
	v_lshlrev_b32_e32 v157, 16, v143
	v_and_b32_e32 v143, 0xffff0000, v143
	v_mul_f32_e32 v160, v29, v143
	v_mul_f32_e32 v143, v33, v143
	v_add_f32_e32 v142, 0, v142
	v_fmac_f32_e32 v143, v32, v157
	v_add_f32_e32 v142, v143, v142
	v_lshlrev_b32_e32 v143, 16, v144
	v_and_b32_e32 v144, 0xffff0000, v144
	v_fmac_f32_e32 v160, v28, v157
	v_mul_f32_e32 v157, v19, v144
	v_mul_f32_e32 v144, v23, v144
	v_fmac_f32_e32 v144, v22, v143
	v_add_f32_e32 v142, v144, v142
	v_and_b32_e32 v144, 0xffff0000, v145
	v_fmac_f32_e32 v157, v18, v143
	v_lshlrev_b32_e32 v143, 16, v145
	v_mul_f32_e32 v145, v21, v144
	v_mul_f32_e32 v144, v25, v144
	v_fmac_f32_e32 v145, v20, v143
	v_fmac_f32_e32 v144, v24, v143
	s_waitcnt lgkmcnt(0)
	v_lshlrev_b32_e32 v143, 16, v34
	v_and_b32_e32 v34, 0xffff0000, v34
	v_add_f32_e32 v142, v144, v142
	v_mul_f32_e32 v144, v11, v34
	v_mul_f32_e32 v34, v15, v34
	v_fmac_f32_e32 v34, v14, v143
	v_add_f32_e32 v34, v34, v142
	v_lshlrev_b32_e32 v142, 16, v35
	v_and_b32_e32 v35, 0xffff0000, v35
	v_fmac_f32_e32 v144, v10, v143
	v_mul_f32_e32 v143, v13, v35
	v_mul_f32_e32 v35, v17, v35
	v_add_f32_e32 v158, 0, v158
	v_fmac_f32_e32 v35, v16, v142
	v_add_f32_e32 v158, v160, v158
	v_add_f32_e32 v34, v35, v34
	v_lshlrev_b32_e32 v35, 16, v36
	v_and_b32_e32 v36, 0xffff0000, v36
	v_add_f32_e32 v157, v157, v158
	v_fmac_f32_e32 v143, v12, v142
	v_mul_f32_e32 v142, v7, v36
	v_mul_f32_e32 v36, v3, v36
	v_add_f32_e32 v145, v145, v157
	v_fmac_f32_e32 v36, v2, v35
	v_add_f32_e32 v144, v144, v145
	v_add_f32_e32 v34, v36, v34
	v_and_b32_e32 v36, 0xffff0000, v37
	v_add_f32_e32 v143, v143, v144
	v_fmac_f32_e32 v142, v6, v35
	v_lshlrev_b32_e32 v35, 16, v37
	v_mul_f32_e32 v37, v9, v36
	v_add_f32_e32 v142, v142, v143
	v_fmac_f32_e32 v37, v8, v35
	v_mul_f32_e32 v36, v5, v36
	v_add_f32_e32 v37, v37, v142
	v_fmac_f32_e32 v36, v4, v35
	v_add_f32_e32 v35, v36, v34
	v_add_f32_dpp v34, v37, v37 quad_perm:[1,0,3,2] row_mask:0xf bank_mask:0xf bound_ctrl:1
	s_nop 0
	v_add_f32_dpp v35, v35, v35 quad_perm:[1,0,3,2] row_mask:0xf bank_mask:0xf bound_ctrl:1
	v_add_f32_dpp v34, v34, v34 quad_perm:[2,3,0,1] row_mask:0xf bank_mask:0xf bound_ctrl:1
	s_nop 0
	v_add_f32_dpp v35, v35, v35 quad_perm:[2,3,0,1] row_mask:0xf bank_mask:0xf bound_ctrl:1
	v_add_f32_dpp v34, v34, v34 row_half_mirror row_mask:0xf bank_mask:0xf bound_ctrl:1
	s_nop 0
	v_add_f32_dpp v35, v35, v35 row_half_mirror row_mask:0xf bank_mask:0xf bound_ctrl:1
	v_add_f32_dpp v34, v34, v34 row_mirror row_mask:0xf bank_mask:0xf bound_ctrl:1
	v_mov_b32_e32 v36, v34
	s_nop 1
	v_permlane16_swap_b32 v36, v34
	v_add_f32_dpp v35, v35, v35 row_mirror row_mask:0xf bank_mask:0xf bound_ctrl:1
	v_add_f32_e32 v34, v36, v34
	v_mov_b32_e32 v36, v34
	v_mov_b32_e32 v37, v35
	s_nop 1
	v_permlane32_swap_b32 v36, v34
	s_nop 1
	v_permlane16_swap_b32 v37, v35
	s_nop 0
	v_add_f32_e32 v35, v37, v35
	v_mov_b32_e32 v37, v35
	s_nop 1
	v_permlane32_swap_b32 v37, v35
	s_nop 0
	v_add_f32_e32 v35, v37, v35
	v_mul_f32_e32 v35, 0xbfb8aa3b, v35
	v_exp_f32_e32 v35, v35
	s_nop 0
	v_add_f32_e32 v35, 1.0, v35
	v_rcp_f32_e32 v35, v35
	s_and_saveexec_b64 s[64:65], s[12:13]
	s_cbranch_execz .LBB0_424
	v_add_f32_e32 v34, v36, v34
	v_add_f32_e32 v34, v141, v34
	v_mul_f32_e64 v36, |v34|, s4
	v_exp_f32_e32 v36, v36
	v_max_f32_e32 v34, 0, v34
	v_add_f32_e32 v36, 1.0, v36
	v_cmp_gt_f32_e32 vcc, s43, v36
	s_nop 1
	v_cndmask_b32_e64 v37, 0, 32, vcc
	v_ldexp_f32 v36, v36, v37
	v_log_f32_e32 v36, v36
	v_lshl_add_u32 v37, s84, 2, v241
	v_mul_f32_e32 v142, 0x3f317217, v36
	v_fma_f32 v142, v36, s46, -v142
	v_fmac_f32_e32 v142, 0x3377d1cf, v36
	v_fmac_f32_e32 v142, 0x3f317217, v36
	v_cmp_lt_f32_e64 s[16:17], |v36|, s39
	s_nop 1
	v_cndmask_b32_e64 v36, v36, v142, s[16:17]
	v_cndmask_b32_e32 v142, 0, v236, vcc
	v_sub_f32_e32 v36, v36, v142
	v_add_f32_e32 v34, v34, v36
	v_mul_f32_e64 v34, v34, -v42
	ds_write2st64_b32 v37, v34, v35 offset1:1
.LBB0_424:
	s_or_b64 exec, exec, s[64:65]
	s_add_u32 s16, s44, s85
	s_addc_u32 s17, s61, 0
	s_lshl_b64 s[16:17], s[16:17], 11
	v_lshl_add_u64 v[36:37], v[112:113], 0, s[16:17]
	ds_read_b128 v[142:145], v164 offset:2048
	ds_read_b128 v[242:245], v164 offset:3072
	s_waitcnt lgkmcnt(1)
	v_and_b32_e32 v36, 0xffff0000, v142
	v_lshlrev_b32_e32 v34, 16, v142
	v_mul_f32_e32 v37, v27, v36
	v_mul_f32_e32 v36, v31, v36
	v_fmac_f32_e32 v36, v30, v34
	v_and_b32_e32 v142, 0xffff0000, v143
	v_fmac_f32_e32 v37, v26, v34
	v_add_f32_e32 v34, 0, v36
	v_lshlrev_b32_e32 v36, 16, v143
	v_mul_f32_e32 v143, v29, v142
	v_mul_f32_e32 v142, v33, v142
	v_fmac_f32_e32 v142, v32, v36
	v_add_f32_e32 v37, 0, v37
	v_fmac_f32_e32 v143, v28, v36
	v_add_f32_e32 v34, v142, v34
	v_and_b32_e32 v142, 0xffff0000, v144
	v_add_f32_e32 v37, v143, v37
	v_lshlrev_b32_e32 v36, 16, v144
	v_mul_f32_e32 v143, v19, v142
	v_mul_f32_e32 v142, v23, v142
	v_fmac_f32_e32 v142, v22, v36
	v_fmac_f32_e32 v143, v18, v36
	v_add_f32_e32 v34, v142, v34
	v_and_b32_e32 v142, 0xffff0000, v145
	v_add_f32_e32 v37, v143, v37
	v_lshlrev_b32_e32 v36, 16, v145
	v_mul_f32_e32 v143, v21, v142
	v_mul_f32_e32 v142, v25, v142
	v_fmac_f32_e32 v142, v24, v36
	v_fmac_f32_e32 v143, v20, v36
	v_add_f32_e32 v34, v142, v34
	s_waitcnt lgkmcnt(0)
	v_and_b32_e32 v142, 0xffff0000, v242
	v_add_f32_e32 v37, v143, v37
	v_lshlrev_b32_e32 v36, 16, v242
	v_mul_f32_e32 v143, v11, v142
	v_mul_f32_e32 v142, v15, v142
	v_fmac_f32_e32 v142, v14, v36
	v_fmac_f32_e32 v143, v10, v36
	v_add_f32_e32 v34, v142, v34
	v_and_b32_e32 v142, 0xffff0000, v243
	v_add_f32_e32 v37, v143, v37
	v_lshlrev_b32_e32 v36, 16, v243
	v_mul_f32_e32 v143, v13, v142
	v_mul_f32_e32 v142, v17, v142
	v_fmac_f32_e32 v142, v16, v36
	v_fmac_f32_e32 v143, v12, v36
	v_add_f32_e32 v34, v142, v34
	v_and_b32_e32 v142, 0xffff0000, v244
	v_add_f32_e32 v37, v143, v37
	v_lshlrev_b32_e32 v36, 16, v244
	v_mul_f32_e32 v143, v7, v142
	v_mul_f32_e32 v142, v3, v142
	v_fmac_f32_e32 v142, v2, v36
	v_fmac_f32_e32 v143, v6, v36
	v_add_f32_e32 v34, v142, v34
	v_and_b32_e32 v142, 0xffff0000, v245
	v_add_f32_e32 v37, v143, v37
	v_lshlrev_b32_e32 v36, 16, v245
	v_mul_f32_e32 v143, v9, v142
	v_fmac_f32_e32 v143, v8, v36
	v_mul_f32_e32 v142, v5, v142
	v_add_f32_e32 v37, v143, v37
	v_fmac_f32_e32 v142, v4, v36
	v_add_f32_e32 v36, v142, v34
	v_add_f32_dpp v34, v37, v37 quad_perm:[1,0,3,2] row_mask:0xf bank_mask:0xf bound_ctrl:1
	s_nop 0
	v_add_f32_dpp v36, v36, v36 quad_perm:[1,0,3,2] row_mask:0xf bank_mask:0xf bound_ctrl:1
	v_add_f32_dpp v34, v34, v34 quad_perm:[2,3,0,1] row_mask:0xf bank_mask:0xf bound_ctrl:1
	s_nop 0
	v_add_f32_dpp v36, v36, v36 quad_perm:[2,3,0,1] row_mask:0xf bank_mask:0xf bound_ctrl:1
	v_add_f32_dpp v34, v34, v34 row_half_mirror row_mask:0xf bank_mask:0xf bound_ctrl:1
	s_nop 0
	v_add_f32_dpp v36, v36, v36 row_half_mirror row_mask:0xf bank_mask:0xf bound_ctrl:1
	v_add_f32_dpp v34, v34, v34 row_mirror row_mask:0xf bank_mask:0xf bound_ctrl:1
	v_mov_b32_e32 v37, v34
	s_nop 1
	v_permlane16_swap_b32 v37, v34
	v_add_f32_dpp v36, v36, v36 row_mirror row_mask:0xf bank_mask:0xf bound_ctrl:1
	v_add_f32_e32 v34, v37, v34
	v_mov_b32_e32 v37, v34
	v_mov_b32_e32 v142, v36
	s_nop 1
	v_permlane32_swap_b32 v37, v34
	s_nop 1
	v_permlane16_swap_b32 v142, v36
	s_nop 0
	v_add_f32_e32 v36, v142, v36
	v_mov_b32_e32 v142, v36
	s_nop 1
	v_permlane32_swap_b32 v142, v36
	s_nop 0
	v_add_f32_e32 v36, v142, v36
	v_mul_f32_e32 v36, 0xbfb8aa3b, v36
	v_exp_f32_e32 v36, v36
	s_nop 0
	v_add_f32_e32 v36, 1.0, v36
	v_rcp_f32_e32 v36, v36
	s_and_saveexec_b64 s[64:65], s[12:13]
	s_cbranch_execz .LBB0_426
	v_add_f32_e32 v34, v37, v34
	v_add_f32_e32 v34, v141, v34
	v_mul_f32_e64 v37, |v34|, s4
	v_exp_f32_e32 v37, v37
	v_max_f32_e32 v34, 0, v34
	v_add_f32_e32 v37, 1.0, v37
	v_cmp_gt_f32_e32 vcc, s43, v37
	s_nop 1
	v_cndmask_b32_e64 v142, 0, 32, vcc
	v_ldexp_f32 v37, v37, v142
	v_log_f32_e32 v37, v37
	v_lshl_add_u32 v142, s85, 2, v241
	v_mul_f32_e32 v143, 0x3f317217, v37
	v_fma_f32 v143, v37, s46, -v143
	v_fmac_f32_e32 v143, 0x3377d1cf, v37
	v_fmac_f32_e32 v143, 0x3f317217, v37
	v_cmp_lt_f32_e64 s[16:17], |v37|, s39
	s_nop 1
	v_cndmask_b32_e64 v37, v37, v143, s[16:17]
	v_cndmask_b32_e32 v143, 0, v236, vcc
	v_sub_f32_e32 v37, v37, v143
	v_add_f32_e32 v34, v34, v37
	v_mul_f32_e64 v34, v34, -v42
	ds_write2st64_b32 v142, v34, v36 offset1:1
.LBB0_426:
	s_or_b64 exec, exec, s[64:65]
	s_add_u32 s16, s44, s86
	s_addc_u32 s17, s61, 0
	s_lshl_b64 s[16:17], s[16:17], 11
	v_lshl_add_u64 v[160:161], v[112:113], 0, s[16:17]
	ds_read_b128 v[142:145], v164 offset:4096
	ds_read_b128 v[242:245], v164 offset:5120
	s_waitcnt lgkmcnt(1)
	v_and_b32_e32 v37, 0xffff0000, v142
	v_lshlrev_b32_e32 v34, 16, v142
	v_mul_f32_e32 v142, v27, v37
	v_mul_f32_e32 v37, v31, v37
	v_fmac_f32_e32 v37, v30, v34
	v_fmac_f32_e32 v142, v26, v34
	v_add_f32_e32 v34, 0, v37
	v_lshlrev_b32_e32 v37, 16, v143
	v_and_b32_e32 v143, 0xffff0000, v143
	v_mul_f32_e32 v157, v29, v143
	v_mul_f32_e32 v143, v33, v143
	v_fmac_f32_e32 v143, v32, v37
	v_add_f32_e32 v34, v143, v34
	v_and_b32_e32 v143, 0xffff0000, v144
	v_fmac_f32_e32 v157, v28, v37
	v_lshlrev_b32_e32 v37, 16, v144
	v_mul_f32_e32 v144, v19, v143
	v_mul_f32_e32 v143, v23, v143
	v_add_f32_e32 v142, 0, v142
	v_fmac_f32_e32 v143, v22, v37
	v_add_f32_e32 v142, v157, v142
	v_fmac_f32_e32 v144, v18, v37
	v_add_f32_e32 v34, v143, v34
	v_and_b32_e32 v143, 0xffff0000, v145
	v_add_f32_e32 v142, v144, v142
	v_lshlrev_b32_e32 v37, 16, v145
	v_mul_f32_e32 v144, v21, v143
	v_mul_f32_e32 v143, v25, v143
	v_fmac_f32_e32 v143, v24, v37
	v_fmac_f32_e32 v144, v20, v37
	v_add_f32_e32 v34, v143, v34
	s_waitcnt lgkmcnt(0)
	v_and_b32_e32 v143, 0xffff0000, v242
	v_add_f32_e32 v142, v144, v142
	v_lshlrev_b32_e32 v37, 16, v242
	v_mul_f32_e32 v144, v11, v143
	v_mul_f32_e32 v143, v15, v143
	v_fmac_f32_e32 v143, v14, v37
	v_fmac_f32_e32 v144, v10, v37
	v_add_f32_e32 v34, v143, v34
	v_and_b32_e32 v143, 0xffff0000, v243
	v_add_f32_e32 v142, v144, v142
	v_lshlrev_b32_e32 v37, 16, v243
	v_mul_f32_e32 v144, v13, v143
	v_mul_f32_e32 v143, v17, v143
	v_fmac_f32_e32 v143, v16, v37
	v_fmac_f32_e32 v144, v12, v37
	v_add_f32_e32 v34, v143, v34
	v_and_b32_e32 v143, 0xffff0000, v244
	v_add_f32_e32 v142, v144, v142
	v_lshlrev_b32_e32 v37, 16, v244
	v_mul_f32_e32 v144, v7, v143
	v_mul_f32_e32 v143, v3, v143
	v_fmac_f32_e32 v143, v2, v37
	v_fmac_f32_e32 v144, v6, v37
	v_add_f32_e32 v34, v143, v34
	v_and_b32_e32 v143, 0xffff0000, v245
	v_add_f32_e32 v142, v144, v142
	v_lshlrev_b32_e32 v37, 16, v245
	v_mul_f32_e32 v144, v9, v143
	v_fmac_f32_e32 v144, v8, v37
	v_mul_f32_e32 v143, v5, v143
	v_add_f32_e32 v142, v144, v142
	v_fmac_f32_e32 v143, v4, v37
	v_add_f32_e32 v37, v143, v34
	v_add_f32_dpp v34, v142, v142 quad_perm:[1,0,3,2] row_mask:0xf bank_mask:0xf bound_ctrl:1
	s_nop 0
	v_add_f32_dpp v37, v37, v37 quad_perm:[1,0,3,2] row_mask:0xf bank_mask:0xf bound_ctrl:1
	v_add_f32_dpp v34, v34, v34 quad_perm:[2,3,0,1] row_mask:0xf bank_mask:0xf bound_ctrl:1
	s_nop 0
	v_add_f32_dpp v37, v37, v37 quad_perm:[2,3,0,1] row_mask:0xf bank_mask:0xf bound_ctrl:1
	v_add_f32_dpp v34, v34, v34 row_half_mirror row_mask:0xf bank_mask:0xf bound_ctrl:1
	s_nop 0
	v_add_f32_dpp v37, v37, v37 row_half_mirror row_mask:0xf bank_mask:0xf bound_ctrl:1
	v_add_f32_dpp v34, v34, v34 row_mirror row_mask:0xf bank_mask:0xf bound_ctrl:1
	v_mov_b32_e32 v142, v34
	s_nop 1
	v_permlane16_swap_b32 v142, v34
	v_add_f32_dpp v37, v37, v37 row_mirror row_mask:0xf bank_mask:0xf bound_ctrl:1
	v_add_f32_e32 v34, v142, v34
	v_mov_b32_e32 v142, v34
	v_mov_b32_e32 v143, v37
	s_nop 1
	v_permlane32_swap_b32 v142, v34
	s_nop 1
	v_permlane16_swap_b32 v143, v37
	s_nop 0
	v_add_f32_e32 v37, v143, v37
	v_mov_b32_e32 v143, v37
	s_nop 1
	v_permlane32_swap_b32 v143, v37
	s_nop 0
	v_add_f32_e32 v37, v143, v37
	v_mul_f32_e32 v37, 0xbfb8aa3b, v37
	v_exp_f32_e32 v37, v37
	s_nop 0
	v_add_f32_e32 v37, 1.0, v37
	v_rcp_f32_e32 v37, v37
	s_and_saveexec_b64 s[64:65], s[12:13]
	s_cbranch_execz .LBB0_428
	v_add_f32_e32 v34, v142, v34
	v_add_f32_e32 v34, v141, v34
	v_mul_f32_e64 v142, |v34|, s4
	v_exp_f32_e32 v142, v142
	v_max_f32_e32 v34, 0, v34
	v_add_f32_e32 v142, 1.0, v142
	v_cmp_gt_f32_e32 vcc, s43, v142
	s_nop 1
	v_cndmask_b32_e64 v143, 0, 32, vcc
	v_ldexp_f32 v142, v142, v143
	v_log_f32_e32 v142, v142
	v_lshl_add_u32 v143, s86, 2, v241
	v_mul_f32_e32 v144, 0x3f317217, v142
	v_fma_f32 v144, v142, s46, -v144
	v_fmac_f32_e32 v144, 0x3377d1cf, v142
	v_fmac_f32_e32 v144, 0x3f317217, v142
	v_cmp_lt_f32_e64 s[16:17], |v142|, s39
	s_nop 1
	v_cndmask_b32_e64 v142, v142, v144, s[16:17]
	v_cndmask_b32_e32 v144, 0, v236, vcc
	v_sub_f32_e32 v142, v142, v144
	v_add_f32_e32 v34, v34, v142
	v_mul_f32_e64 v34, v34, -v42
	ds_write2st64_b32 v143, v34, v37 offset1:1
.LBB0_428:
	s_or_b64 exec, exec, s[64:65]
	s_add_u32 s16, s44, s87
	s_addc_u32 s17, s61, 0
	s_lshl_b64 s[16:17], s[16:17], 11
	v_lshl_add_u64 v[160:161], v[112:113], 0, s[16:17]
	ds_read_b128 v[142:145], v164 offset:6144
	ds_read_b128 v[242:245], v164 offset:7168
	s_waitcnt lgkmcnt(1)
	v_lshlrev_b32_e32 v34, 16, v142
	v_and_b32_e32 v142, 0xffff0000, v142
	v_mul_f32_e32 v157, v27, v142
	v_mul_f32_e32 v142, v31, v142
	v_fmac_f32_e32 v142, v30, v34
	v_fmac_f32_e32 v157, v26, v34
	v_add_f32_e32 v34, 0, v142
	v_lshlrev_b32_e32 v142, 16, v143
	v_and_b32_e32 v143, 0xffff0000, v143
	v_mul_f32_e32 v158, v29, v143
	v_mul_f32_e32 v143, v33, v143
	v_fmac_f32_e32 v143, v32, v142
	v_add_f32_e32 v34, v143, v34
	v_and_b32_e32 v143, 0xffff0000, v144
	v_fmac_f32_e32 v158, v28, v142
	v_lshlrev_b32_e32 v142, 16, v144
	v_mul_f32_e32 v144, v19, v143
	v_mul_f32_e32 v143, v23, v143
	v_fmac_f32_e32 v143, v22, v142
	v_add_f32_e32 v34, v143, v34
	v_and_b32_e32 v143, 0xffff0000, v145
	v_add_f32_e32 v157, 0, v157
	v_fmac_f32_e32 v144, v18, v142
	v_lshlrev_b32_e32 v142, 16, v145
	v_mul_f32_e32 v145, v21, v143
	v_mul_f32_e32 v143, v25, v143
	v_add_f32_e32 v157, v158, v157
	v_fmac_f32_e32 v143, v24, v142
	v_add_f32_e32 v144, v144, v157
	v_fmac_f32_e32 v145, v20, v142
	v_add_f32_e32 v34, v143, v34
	s_waitcnt lgkmcnt(0)
	v_and_b32_e32 v143, 0xffff0000, v242
	v_add_f32_e32 v144, v145, v144
	v_lshlrev_b32_e32 v142, 16, v242
	v_mul_f32_e32 v145, v11, v143
	v_mul_f32_e32 v143, v15, v143
	v_fmac_f32_e32 v143, v14, v142
	v_fmac_f32_e32 v145, v10, v142
	v_add_f32_e32 v34, v143, v34
	v_and_b32_e32 v143, 0xffff0000, v243
	v_add_f32_e32 v144, v145, v144
	v_lshlrev_b32_e32 v142, 16, v243
	v_mul_f32_e32 v145, v13, v143
	v_mul_f32_e32 v143, v17, v143
	v_fmac_f32_e32 v143, v16, v142
	v_fmac_f32_e32 v145, v12, v142
	v_add_f32_e32 v34, v143, v34
	v_and_b32_e32 v143, 0xffff0000, v244
	v_add_f32_e32 v144, v145, v144
	v_lshlrev_b32_e32 v142, 16, v244
	v_mul_f32_e32 v145, v7, v143
	v_mul_f32_e32 v143, v3, v143
	v_fmac_f32_e32 v143, v2, v142
	v_fmac_f32_e32 v145, v6, v142
	v_add_f32_e32 v34, v143, v34
	v_and_b32_e32 v143, 0xffff0000, v245
	v_add_f32_e32 v144, v145, v144
	v_lshlrev_b32_e32 v142, 16, v245
	v_mul_f32_e32 v145, v9, v143
	v_fmac_f32_e32 v145, v8, v142
	v_add_f32_e32 v144, v145, v144
	v_mul_f32_e32 v143, v5, v143
	v_fmac_f32_e32 v143, v4, v142
	v_add_f32_dpp v142, v144, v144 quad_perm:[1,0,3,2] row_mask:0xf bank_mask:0xf bound_ctrl:1
	v_add_f32_e32 v34, v143, v34
	s_nop 0
	v_add_f32_dpp v142, v142, v142 quad_perm:[2,3,0,1] row_mask:0xf bank_mask:0xf bound_ctrl:1
	v_add_f32_dpp v34, v34, v34 quad_perm:[1,0,3,2] row_mask:0xf bank_mask:0xf bound_ctrl:1
	s_nop 0
	v_add_f32_dpp v142, v142, v142 row_half_mirror row_mask:0xf bank_mask:0xf bound_ctrl:1
	v_add_f32_dpp v34, v34, v34 quad_perm:[2,3,0,1] row_mask:0xf bank_mask:0xf bound_ctrl:1
	s_nop 0
	v_add_f32_dpp v142, v142, v142 row_mirror row_mask:0xf bank_mask:0xf bound_ctrl:1
	v_mov_b32_e32 v143, v142
	s_nop 1
	v_permlane16_swap_b32 v143, v142
	v_add_f32_dpp v34, v34, v34 row_half_mirror row_mask:0xf bank_mask:0xf bound_ctrl:1
	v_add_f32_e32 v142, v143, v142
	v_mov_b32_e32 v143, v142
	v_add_f32_dpp v34, v34, v34 row_mirror row_mask:0xf bank_mask:0xf bound_ctrl:1
	v_mov_b32_e32 v144, v34
	s_nop 1
	v_permlane32_swap_b32 v143, v142
	s_nop 1
	v_permlane16_swap_b32 v144, v34
	s_nop 0
	v_add_f32_e32 v34, v144, v34
	v_mov_b32_e32 v144, v34
	s_nop 1
	v_permlane32_swap_b32 v144, v34
	s_nop 0
	v_add_f32_e32 v34, v144, v34
	v_mul_f32_e32 v34, 0xbfb8aa3b, v34
	v_exp_f32_e32 v34, v34
	s_nop 0
	v_add_f32_e32 v34, 1.0, v34
	v_rcp_f32_e32 v34, v34
	s_and_saveexec_b64 s[64:65], s[12:13]
	s_cbranch_execz .LBB0_430
	v_add_f32_e32 v142, v143, v142
	v_add_f32_e32 v142, v141, v142
	v_mul_f32_e64 v143, |v142|, s4
	v_exp_f32_e32 v143, v143
	v_max_f32_e32 v142, 0, v142
	v_add_f32_e32 v143, 1.0, v143
	v_cmp_gt_f32_e32 vcc, s43, v143
	s_nop 1
	v_cndmask_b32_e64 v144, 0, 32, vcc
	v_ldexp_f32 v143, v143, v144
	v_log_f32_e32 v143, v143
	v_lshl_add_u32 v144, s87, 2, v241
	v_mul_f32_e32 v145, 0x3f317217, v143
	v_fma_f32 v145, v143, s46, -v145
	v_fmac_f32_e32 v145, 0x3377d1cf, v143
	v_fmac_f32_e32 v145, 0x3f317217, v143
	v_cmp_lt_f32_e64 s[16:17], |v143|, s39
	s_nop 1
	v_cndmask_b32_e64 v143, v143, v145, s[16:17]
	v_cndmask_b32_e32 v145, 0, v236, vcc
	v_sub_f32_e32 v143, v143, v145
	v_add_f32_e32 v142, v142, v143
	v_mul_f32_e64 v142, v142, -v42
	ds_write2st64_b32 v144, v142, v34 offset1:1
.LBB0_430:
	s_or_b64 exec, exec, s[64:65]
	s_add_u32 s16, s44, s88
	s_addc_u32 s17, s61, 0
	s_lshl_b64 s[16:17], s[16:17], 11
	v_lshl_add_u64 v[160:161], v[112:113], 0, s[16:17]
	ds_read_b128 v[142:145], v164 offset:8192
	ds_read_b128 v[242:245], v164 offset:9216
	s_waitcnt lgkmcnt(1)
	v_lshlrev_b32_e32 v157, 16, v142
	v_and_b32_e32 v142, 0xffff0000, v142
	v_mul_f32_e32 v158, v27, v142
	v_mul_f32_e32 v142, v31, v142
	v_fmac_f32_e32 v158, v26, v157
	v_fmac_f32_e32 v142, v30, v157
	v_lshlrev_b32_e32 v157, 16, v143
	v_and_b32_e32 v143, 0xffff0000, v143
	v_mul_f32_e32 v160, v29, v143
	v_mul_f32_e32 v143, v33, v143
	v_add_f32_e32 v142, 0, v142
	v_fmac_f32_e32 v143, v32, v157
	v_add_f32_e32 v142, v143, v142
	v_lshlrev_b32_e32 v143, 16, v144
	v_and_b32_e32 v144, 0xffff0000, v144
	v_fmac_f32_e32 v160, v28, v157
	v_mul_f32_e32 v157, v19, v144
	v_mul_f32_e32 v144, v23, v144
	v_fmac_f32_e32 v144, v22, v143
	v_add_f32_e32 v142, v144, v142
	v_and_b32_e32 v144, 0xffff0000, v145
	v_add_f32_e32 v158, 0, v158
	v_fmac_f32_e32 v157, v18, v143
	v_lshlrev_b32_e32 v143, 16, v145
	v_mul_f32_e32 v145, v21, v144
	v_mul_f32_e32 v144, v25, v144
	v_add_f32_e32 v158, v160, v158
	v_fmac_f32_e32 v144, v24, v143
	v_add_f32_e32 v157, v157, v158
	v_fmac_f32_e32 v145, v20, v143
	v_add_f32_e32 v142, v144, v142
	s_waitcnt lgkmcnt(0)
	v_and_b32_e32 v144, 0xffff0000, v242
	v_add_f32_e32 v145, v145, v157
	v_lshlrev_b32_e32 v143, 16, v242
	v_mul_f32_e32 v157, v11, v144
	v_mul_f32_e32 v144, v15, v144
	v_fmac_f32_e32 v144, v14, v143
	v_fmac_f32_e32 v157, v10, v143
	v_add_f32_e32 v142, v144, v142
	v_and_b32_e32 v144, 0xffff0000, v243
	v_add_f32_e32 v145, v157, v145
	v_lshlrev_b32_e32 v143, 16, v243
	v_mul_f32_e32 v157, v13, v144
	v_mul_f32_e32 v144, v17, v144
	v_fmac_f32_e32 v144, v16, v143
	v_fmac_f32_e32 v157, v12, v143
	v_add_f32_e32 v142, v144, v142
	v_and_b32_e32 v144, 0xffff0000, v244
	v_add_f32_e32 v145, v157, v145
	v_lshlrev_b32_e32 v143, 16, v244
	v_mul_f32_e32 v157, v7, v144
	v_mul_f32_e32 v144, v3, v144
	v_fmac_f32_e32 v144, v2, v143
	v_fmac_f32_e32 v157, v6, v143
	v_add_f32_e32 v142, v144, v142
	v_and_b32_e32 v144, 0xffff0000, v245
	v_add_f32_e32 v145, v157, v145
	v_lshlrev_b32_e32 v143, 16, v245
	v_mul_f32_e32 v157, v9, v144
	v_fmac_f32_e32 v157, v8, v143
	v_add_f32_e32 v145, v157, v145
	v_mul_f32_e32 v144, v5, v144
	v_fmac_f32_e32 v144, v4, v143
	v_add_f32_dpp v143, v145, v145 quad_perm:[1,0,3,2] row_mask:0xf bank_mask:0xf bound_ctrl:1
	v_add_f32_e32 v142, v144, v142
	s_nop 0
	v_add_f32_dpp v143, v143, v143 quad_perm:[2,3,0,1] row_mask:0xf bank_mask:0xf bound_ctrl:1
	v_add_f32_dpp v142, v142, v142 quad_perm:[1,0,3,2] row_mask:0xf bank_mask:0xf bound_ctrl:1
	s_nop 0
	v_add_f32_dpp v143, v143, v143 row_half_mirror row_mask:0xf bank_mask:0xf bound_ctrl:1
	v_add_f32_dpp v142, v142, v142 quad_perm:[2,3,0,1] row_mask:0xf bank_mask:0xf bound_ctrl:1
	s_nop 0
	v_add_f32_dpp v143, v143, v143 row_mirror row_mask:0xf bank_mask:0xf bound_ctrl:1
	v_mov_b32_e32 v144, v143
	s_nop 1
	v_permlane16_swap_b32 v144, v143
	v_add_f32_dpp v142, v142, v142 row_half_mirror row_mask:0xf bank_mask:0xf bound_ctrl:1
	v_add_f32_e32 v143, v144, v143
	v_mov_b32_e32 v144, v143
	v_add_f32_dpp v142, v142, v142 row_mirror row_mask:0xf bank_mask:0xf bound_ctrl:1
	v_mov_b32_e32 v145, v142
	s_nop 1
	v_permlane32_swap_b32 v144, v143
	s_nop 1
	v_permlane16_swap_b32 v145, v142
	s_nop 0
	v_add_f32_e32 v142, v145, v142
	v_mov_b32_e32 v145, v142
	s_nop 1
	v_permlane32_swap_b32 v145, v142
	s_nop 0
	v_add_f32_e32 v142, v145, v142
	v_mul_f32_e32 v142, 0xbfb8aa3b, v142
	v_exp_f32_e32 v142, v142
	s_nop 0
	v_add_f32_e32 v142, 1.0, v142
	v_rcp_f32_e32 v142, v142
	s_and_saveexec_b64 s[64:65], s[12:13]
	s_cbranch_execz .LBB0_432
	v_add_f32_e32 v143, v144, v143
	v_add_f32_e32 v143, v141, v143
	v_mul_f32_e64 v144, |v143|, s4
	v_exp_f32_e32 v144, v144
	v_max_f32_e32 v143, 0, v143
	v_add_f32_e32 v144, 1.0, v144
	v_cmp_gt_f32_e32 vcc, s43, v144
	s_nop 1
	v_cndmask_b32_e64 v145, 0, 32, vcc
	v_ldexp_f32 v144, v144, v145
	v_log_f32_e32 v144, v144
	v_lshl_add_u32 v145, s88, 2, v241
	v_mul_f32_e32 v157, 0x3f317217, v144
	v_fma_f32 v157, v144, s46, -v157
	v_fmac_f32_e32 v157, 0x3377d1cf, v144
	v_fmac_f32_e32 v157, 0x3f317217, v144
	v_cmp_lt_f32_e64 s[16:17], |v144|, s39
	s_nop 1
	v_cndmask_b32_e64 v144, v144, v157, s[16:17]
	v_cndmask_b32_e32 v157, 0, v236, vcc
	v_sub_f32_e32 v144, v144, v157
	v_add_f32_e32 v143, v143, v144
	v_mul_f32_e64 v143, v143, -v42
	ds_write2st64_b32 v145, v143, v142 offset1:1
.LBB0_432:
	s_or_b64 exec, exec, s[64:65]
	s_add_u32 s16, s44, s89
	s_addc_u32 s17, s61, 0
	s_lshl_b64 s[16:17], s[16:17], 11
	v_lshl_add_u64 v[144:145], v[112:113], 0, s[16:17]
	ds_read_b128 v[242:245], v164 offset:10240
	ds_read_b128 v[246:249], v164 offset:11264
	s_waitcnt lgkmcnt(1)
	v_and_b32_e32 v144, 0xffff0000, v242
	v_lshlrev_b32_e32 v143, 16, v242
	v_mul_f32_e32 v145, v27, v144
	v_mul_f32_e32 v144, v31, v144
	v_fmac_f32_e32 v144, v30, v143
	v_and_b32_e32 v157, 0xffff0000, v243
	v_fmac_f32_e32 v145, v26, v143
	v_add_f32_e32 v143, 0, v144
	v_lshlrev_b32_e32 v144, 16, v243
	v_mul_f32_e32 v158, v29, v157
	v_mul_f32_e32 v157, v33, v157
	v_fmac_f32_e32 v157, v32, v144
	v_add_f32_e32 v145, 0, v145
	v_fmac_f32_e32 v158, v28, v144
	v_add_f32_e32 v143, v157, v143
	v_and_b32_e32 v157, 0xffff0000, v244
	v_add_f32_e32 v145, v158, v145
	v_lshlrev_b32_e32 v144, 16, v244
	v_mul_f32_e32 v158, v19, v157
	v_mul_f32_e32 v157, v23, v157
	v_fmac_f32_e32 v157, v22, v144
	v_fmac_f32_e32 v158, v18, v144
	v_add_f32_e32 v143, v157, v143
	v_and_b32_e32 v157, 0xffff0000, v245
	v_add_f32_e32 v145, v158, v145
	v_lshlrev_b32_e32 v144, 16, v245
	v_mul_f32_e32 v158, v21, v157
	v_mul_f32_e32 v157, v25, v157
	v_fmac_f32_e32 v157, v24, v144
	v_fmac_f32_e32 v158, v20, v144
	v_add_f32_e32 v143, v157, v143
	s_waitcnt lgkmcnt(0)
	v_and_b32_e32 v157, 0xffff0000, v246
	v_add_f32_e32 v145, v158, v145
	v_lshlrev_b32_e32 v144, 16, v246
	v_mul_f32_e32 v158, v11, v157
	v_mul_f32_e32 v157, v15, v157
	v_fmac_f32_e32 v157, v14, v144
	v_fmac_f32_e32 v158, v10, v144
	v_add_f32_e32 v143, v157, v143
	v_and_b32_e32 v157, 0xffff0000, v247
	v_add_f32_e32 v145, v158, v145
	v_lshlrev_b32_e32 v144, 16, v247
	v_mul_f32_e32 v158, v13, v157
	v_mul_f32_e32 v157, v17, v157
	v_fmac_f32_e32 v157, v16, v144
	v_fmac_f32_e32 v158, v12, v144
	v_add_f32_e32 v143, v157, v143
	v_and_b32_e32 v157, 0xffff0000, v248
	v_add_f32_e32 v145, v158, v145
	v_lshlrev_b32_e32 v144, 16, v248
	v_mul_f32_e32 v158, v7, v157
	v_mul_f32_e32 v157, v3, v157
	v_fmac_f32_e32 v157, v2, v144
	v_fmac_f32_e32 v158, v6, v144
	v_add_f32_e32 v143, v157, v143
	v_and_b32_e32 v157, 0xffff0000, v249
	v_add_f32_e32 v145, v158, v145
	v_lshlrev_b32_e32 v144, 16, v249
	v_mul_f32_e32 v158, v9, v157
	v_fmac_f32_e32 v158, v8, v144
	v_add_f32_e32 v145, v158, v145
	v_mul_f32_e32 v157, v5, v157
	v_fmac_f32_e32 v157, v4, v144
	v_add_f32_dpp v144, v145, v145 quad_perm:[1,0,3,2] row_mask:0xf bank_mask:0xf bound_ctrl:1
	v_add_f32_e32 v143, v157, v143
	s_nop 0
	v_add_f32_dpp v144, v144, v144 quad_perm:[2,3,0,1] row_mask:0xf bank_mask:0xf bound_ctrl:1
	v_add_f32_dpp v143, v143, v143 quad_perm:[1,0,3,2] row_mask:0xf bank_mask:0xf bound_ctrl:1
	s_nop 0
	v_add_f32_dpp v144, v144, v144 row_half_mirror row_mask:0xf bank_mask:0xf bound_ctrl:1
	v_add_f32_dpp v143, v143, v143 quad_perm:[2,3,0,1] row_mask:0xf bank_mask:0xf bound_ctrl:1
	s_nop 0
	v_add_f32_dpp v144, v144, v144 row_mirror row_mask:0xf bank_mask:0xf bound_ctrl:1
	v_mov_b32_e32 v145, v144
	s_nop 1
	v_permlane16_swap_b32 v145, v144
	v_add_f32_dpp v143, v143, v143 row_half_mirror row_mask:0xf bank_mask:0xf bound_ctrl:1
	v_add_f32_e32 v144, v145, v144
	v_mov_b32_e32 v145, v144
	v_add_f32_dpp v143, v143, v143 row_mirror row_mask:0xf bank_mask:0xf bound_ctrl:1
	v_mov_b32_e32 v157, v143
	s_nop 1
	v_permlane32_swap_b32 v145, v144
	s_nop 1
	v_permlane16_swap_b32 v157, v143
	s_nop 0
	v_add_f32_e32 v143, v157, v143
	v_mov_b32_e32 v157, v143
	s_nop 1
	v_permlane32_swap_b32 v157, v143
	s_nop 0
	v_add_f32_e32 v143, v157, v143
	v_mul_f32_e32 v143, 0xbfb8aa3b, v143
	v_exp_f32_e32 v143, v143
	s_nop 0
	v_add_f32_e32 v143, 1.0, v143
	v_rcp_f32_e32 v143, v143
	s_and_saveexec_b64 s[64:65], s[12:13]
	s_cbranch_execz .LBB0_434
	v_add_f32_e32 v144, v145, v144
	v_add_f32_e32 v144, v141, v144
	v_mul_f32_e64 v145, |v144|, s4
	v_exp_f32_e32 v145, v145
	v_max_f32_e32 v144, 0, v144
	v_add_f32_e32 v145, 1.0, v145
	v_cmp_gt_f32_e32 vcc, s43, v145
	s_nop 1
	v_cndmask_b32_e64 v157, 0, 32, vcc
	v_ldexp_f32 v145, v145, v157
	v_log_f32_e32 v145, v145
	v_lshl_add_u32 v157, s89, 2, v241
	v_mul_f32_e32 v158, 0x3f317217, v145
	v_fma_f32 v158, v145, s46, -v158
	v_fmac_f32_e32 v158, 0x3377d1cf, v145
	v_fmac_f32_e32 v158, 0x3f317217, v145
	v_cmp_lt_f32_e64 s[16:17], |v145|, s39
	s_nop 1
	v_cndmask_b32_e64 v145, v145, v158, s[16:17]
	v_cndmask_b32_e32 v158, 0, v236, vcc
	v_sub_f32_e32 v145, v145, v158
	v_add_f32_e32 v144, v144, v145
	v_mul_f32_e64 v144, v144, -v42
	ds_write2st64_b32 v157, v144, v143 offset1:1
.LBB0_434:
	s_or_b64 exec, exec, s[64:65]
	s_add_u32 s16, s44, s82
	s_addc_u32 s17, s61, 0
	s_lshl_b64 s[16:17], s[16:17], 11
	v_lshl_add_u64 v[144:145], v[112:113], 0, s[16:17]
	ds_read_b128 v[242:245], v164 offset:12288
	ds_read_b128 v[246:249], v164 offset:13312
	s_waitcnt lgkmcnt(1)
	v_and_b32_e32 v145, 0xffff0000, v242
	v_lshlrev_b32_e32 v144, 16, v242
	v_mul_f32_e32 v157, v27, v145
	v_mul_f32_e32 v145, v31, v145
	v_fmac_f32_e32 v145, v30, v144
	v_and_b32_e32 v158, 0xffff0000, v243
	v_fmac_f32_e32 v157, v26, v144
	v_add_f32_e32 v144, 0, v145
	v_lshlrev_b32_e32 v145, 16, v243
	v_mul_f32_e32 v160, v29, v158
	v_mul_f32_e32 v158, v33, v158
	v_fmac_f32_e32 v158, v32, v145
	v_add_f32_e32 v157, 0, v157
	v_fmac_f32_e32 v160, v28, v145
	v_add_f32_e32 v144, v158, v144
	v_and_b32_e32 v158, 0xffff0000, v244
	v_add_f32_e32 v157, v160, v157
	v_lshlrev_b32_e32 v145, 16, v244
	v_mul_f32_e32 v160, v19, v158
	v_mul_f32_e32 v158, v23, v158
	v_fmac_f32_e32 v158, v22, v145
	v_fmac_f32_e32 v160, v18, v145
	v_add_f32_e32 v144, v158, v144
	v_and_b32_e32 v158, 0xffff0000, v245
	v_add_f32_e32 v157, v160, v157
	v_lshlrev_b32_e32 v145, 16, v245
	v_mul_f32_e32 v160, v21, v158
	v_mul_f32_e32 v158, v25, v158
	v_fmac_f32_e32 v158, v24, v145
	v_fmac_f32_e32 v160, v20, v145
	v_add_f32_e32 v144, v158, v144
	s_waitcnt lgkmcnt(0)
	v_and_b32_e32 v158, 0xffff0000, v246
	v_add_f32_e32 v157, v160, v157
	v_lshlrev_b32_e32 v145, 16, v246
	v_mul_f32_e32 v160, v11, v158
	v_mul_f32_e32 v158, v15, v158
	v_fmac_f32_e32 v158, v14, v145
	v_fmac_f32_e32 v160, v10, v145
	v_add_f32_e32 v144, v158, v144
	v_and_b32_e32 v158, 0xffff0000, v247
	v_add_f32_e32 v157, v160, v157
	v_lshlrev_b32_e32 v145, 16, v247
	v_mul_f32_e32 v160, v13, v158
	v_mul_f32_e32 v158, v17, v158
	v_fmac_f32_e32 v158, v16, v145
	v_fmac_f32_e32 v160, v12, v145
	v_add_f32_e32 v144, v158, v144
	v_and_b32_e32 v158, 0xffff0000, v248
	v_add_f32_e32 v157, v160, v157
	v_lshlrev_b32_e32 v145, 16, v248
	v_mul_f32_e32 v160, v7, v158
	v_mul_f32_e32 v158, v3, v158
	v_fmac_f32_e32 v158, v2, v145
	v_fmac_f32_e32 v160, v6, v145
	v_add_f32_e32 v144, v158, v144
	v_and_b32_e32 v158, 0xffff0000, v249
	v_add_f32_e32 v157, v160, v157
	v_lshlrev_b32_e32 v145, 16, v249
	v_mul_f32_e32 v160, v9, v158
	v_fmac_f32_e32 v160, v8, v145
	v_add_f32_e32 v157, v160, v157
	v_mul_f32_e32 v158, v5, v158
	v_fmac_f32_e32 v158, v4, v145
	v_add_f32_dpp v145, v157, v157 quad_perm:[1,0,3,2] row_mask:0xf bank_mask:0xf bound_ctrl:1
	v_add_f32_e32 v144, v158, v144
	s_nop 0
	v_add_f32_dpp v145, v145, v145 quad_perm:[2,3,0,1] row_mask:0xf bank_mask:0xf bound_ctrl:1
	v_add_f32_dpp v144, v144, v144 quad_perm:[1,0,3,2] row_mask:0xf bank_mask:0xf bound_ctrl:1
	s_nop 0
	v_add_f32_dpp v145, v145, v145 row_half_mirror row_mask:0xf bank_mask:0xf bound_ctrl:1
	v_add_f32_dpp v144, v144, v144 quad_perm:[2,3,0,1] row_mask:0xf bank_mask:0xf bound_ctrl:1
	s_nop 0
	v_add_f32_dpp v145, v145, v145 row_mirror row_mask:0xf bank_mask:0xf bound_ctrl:1
	v_mov_b32_e32 v157, v145
	s_nop 1
	v_permlane16_swap_b32 v157, v145
	v_add_f32_dpp v144, v144, v144 row_half_mirror row_mask:0xf bank_mask:0xf bound_ctrl:1
	v_add_f32_e32 v145, v157, v145
	v_mov_b32_e32 v157, v145
	v_add_f32_dpp v144, v144, v144 row_mirror row_mask:0xf bank_mask:0xf bound_ctrl:1
	v_mov_b32_e32 v158, v144
	s_nop 1
	v_permlane32_swap_b32 v157, v145
	s_nop 1
	v_permlane16_swap_b32 v158, v144
	s_nop 0
	v_add_f32_e32 v144, v158, v144
	v_mov_b32_e32 v158, v144
	s_nop 1
	v_permlane32_swap_b32 v158, v144
	s_nop 0
	v_add_f32_e32 v144, v158, v144
	v_mul_f32_e32 v144, 0xbfb8aa3b, v144
	v_exp_f32_e32 v144, v144
	s_nop 0
	v_add_f32_e32 v144, 1.0, v144
	v_rcp_f32_e32 v144, v144
	s_and_saveexec_b64 s[64:65], s[12:13]
	s_cbranch_execz .LBB0_436
	v_add_f32_e32 v145, v157, v145
	v_add_f32_e32 v145, v141, v145
	v_mul_f32_e64 v157, |v145|, s4
	v_exp_f32_e32 v157, v157
	v_max_f32_e32 v145, 0, v145
	v_add_f32_e32 v157, 1.0, v157
	v_cmp_gt_f32_e32 vcc, s43, v157
	s_nop 1
	v_cndmask_b32_e64 v158, 0, 32, vcc
	v_ldexp_f32 v157, v157, v158
	v_log_f32_e32 v157, v157
	v_lshl_add_u32 v158, s82, 2, v241
	v_mul_f32_e32 v160, 0x3f317217, v157
	v_fma_f32 v160, v157, s46, -v160
	v_fmac_f32_e32 v160, 0x3377d1cf, v157
	v_fmac_f32_e32 v160, 0x3f317217, v157
	v_cmp_lt_f32_e64 s[16:17], |v157|, s39
	s_nop 1
	v_cndmask_b32_e64 v157, v157, v160, s[16:17]
	v_cndmask_b32_e32 v160, 0, v236, vcc
	v_sub_f32_e32 v157, v157, v160
	v_add_f32_e32 v145, v145, v157
	v_mul_f32_e64 v145, v145, -v42
	ds_write2st64_b32 v158, v145, v144 offset1:1
.LBB0_436:
	s_or_b64 exec, exec, s[64:65]
	s_add_u32 s16, s44, s83
	s_addc_u32 s17, s61, 0
	s_lshl_b64 s[16:17], s[16:17], 11
	v_lshl_add_u64 v[160:161], v[112:113], 0, s[16:17]
	ds_read_b128 v[242:245], v164 offset:14336
	ds_read_b128 v[246:249], v164 offset:15360
	s_waitcnt lgkmcnt(1)
	v_and_b32_e32 v157, 0xffff0000, v242
	v_lshlrev_b32_e32 v145, 16, v242
	v_mul_f32_e32 v27, v27, v157
	v_fmac_f32_e32 v27, v26, v145
	v_add_f32_e32 v26, 0, v27
	v_mul_f32_e32 v27, v31, v157
	v_and_b32_e32 v31, 0xffff0000, v243
	v_fmac_f32_e32 v27, v30, v145
	v_lshlrev_b32_e32 v30, 16, v243
	v_mul_f32_e32 v29, v29, v31
	v_fmac_f32_e32 v29, v28, v30
	v_mul_f32_e32 v28, v33, v31
	v_add_f32_e32 v27, 0, v27
	v_add_f32_e32 v26, v29, v26
	v_fmac_f32_e32 v28, v32, v30
	v_and_b32_e32 v29, 0xffff0000, v244
	v_add_f32_e32 v27, v28, v27
	v_lshlrev_b32_e32 v28, 16, v244
	v_mul_f32_e32 v19, v19, v29
	v_fmac_f32_e32 v19, v18, v28
	v_add_f32_e32 v18, v19, v26
	v_mul_f32_e32 v19, v23, v29
	v_and_b32_e32 v23, 0xffff0000, v245
	v_fmac_f32_e32 v19, v22, v28
	v_lshlrev_b32_e32 v22, 16, v245
	v_mul_f32_e32 v21, v21, v23
	v_fmac_f32_e32 v21, v20, v22
	v_mul_f32_e32 v20, v25, v23
	v_add_f32_e32 v19, v19, v27
	v_add_f32_e32 v18, v21, v18
	v_fmac_f32_e32 v20, v24, v22
	s_waitcnt lgkmcnt(0)
	v_and_b32_e32 v21, 0xffff0000, v246
	v_add_f32_e32 v19, v20, v19
	v_lshlrev_b32_e32 v20, 16, v246
	v_mul_f32_e32 v11, v11, v21
	v_fmac_f32_e32 v11, v10, v20
	v_add_f32_e32 v10, v11, v18
	v_mul_f32_e32 v11, v15, v21
	v_and_b32_e32 v15, 0xffff0000, v247
	v_fmac_f32_e32 v11, v14, v20
	v_lshlrev_b32_e32 v14, 16, v247
	v_mul_f32_e32 v13, v13, v15
	v_fmac_f32_e32 v13, v12, v14
	v_mul_f32_e32 v12, v17, v15
	v_add_f32_e32 v11, v11, v19
	v_add_f32_e32 v10, v13, v10
	v_fmac_f32_e32 v12, v16, v14
	v_and_b32_e32 v13, 0xffff0000, v248
	v_add_f32_e32 v11, v12, v11
	v_lshlrev_b32_e32 v12, 16, v248
	v_mul_f32_e32 v7, v7, v13
	v_fmac_f32_e32 v7, v6, v12
	v_mul_f32_e32 v3, v3, v13
	v_add_f32_e32 v6, v7, v10
	v_fmac_f32_e32 v3, v2, v12
	v_and_b32_e32 v7, 0xffff0000, v249
	v_add_f32_e32 v2, v3, v11
	v_lshlrev_b32_e32 v3, 16, v249
	v_mul_f32_e32 v9, v9, v7
	v_fmac_f32_e32 v9, v8, v3
	v_mul_f32_e32 v5, v5, v7
	v_add_f32_e32 v6, v9, v6
	v_fmac_f32_e32 v5, v4, v3
	v_add_f32_e32 v4, v5, v2
	v_add_f32_dpp v2, v6, v6 quad_perm:[1,0,3,2] row_mask:0xf bank_mask:0xf bound_ctrl:1
	s_nop 0
	v_add_f32_dpp v4, v4, v4 quad_perm:[1,0,3,2] row_mask:0xf bank_mask:0xf bound_ctrl:1
	v_add_f32_dpp v2, v2, v2 quad_perm:[2,3,0,1] row_mask:0xf bank_mask:0xf bound_ctrl:1
	s_nop 0
	v_add_f32_dpp v4, v4, v4 quad_perm:[2,3,0,1] row_mask:0xf bank_mask:0xf bound_ctrl:1
	v_add_f32_dpp v2, v2, v2 row_half_mirror row_mask:0xf bank_mask:0xf bound_ctrl:1
	s_nop 0
	v_add_f32_dpp v4, v4, v4 row_half_mirror row_mask:0xf bank_mask:0xf bound_ctrl:1
	v_add_f32_dpp v2, v2, v2 row_mirror row_mask:0xf bank_mask:0xf bound_ctrl:1
	v_mov_b32_e32 v3, v2
	s_nop 1
	v_permlane16_swap_b32 v3, v2
	v_add_f32_dpp v4, v4, v4 row_mirror row_mask:0xf bank_mask:0xf bound_ctrl:1
	v_add_f32_e32 v2, v3, v2
	v_mov_b32_e32 v3, v2
	v_mov_b32_e32 v5, v4
	s_nop 1
	v_permlane32_swap_b32 v3, v2
	s_nop 1
	v_permlane16_swap_b32 v5, v4
	s_nop 0
	v_add_f32_e32 v4, v5, v4
	v_mov_b32_e32 v5, v4
	s_nop 1
	v_permlane32_swap_b32 v5, v4
	s_nop 0
	v_add_f32_e32 v4, v5, v4
	v_mul_f32_e32 v4, 0xbfb8aa3b, v4
	v_exp_f32_e32 v4, v4
	s_nop 0
	v_add_f32_e32 v4, 1.0, v4
	v_rcp_f32_e32 v145, v4
	s_and_saveexec_b64 s[64:65], s[12:13]
	s_cbranch_execz .LBB0_438
	v_add_f32_e32 v2, v3, v2
	v_add_f32_e32 v2, v141, v2
	v_mul_f32_e64 v3, |v2|, s4
	v_exp_f32_e32 v3, v3
	v_max_f32_e32 v2, 0, v2
	v_add_f32_e32 v3, 1.0, v3
	v_cmp_gt_f32_e32 vcc, s43, v3
	s_nop 1
	v_cndmask_b32_e64 v4, 0, 32, vcc
	v_ldexp_f32 v3, v3, v4
	v_log_f32_e32 v3, v3
	v_lshl_add_u32 v4, s83, 2, v241
	v_mul_f32_e32 v5, 0x3f317217, v3
	v_fma_f32 v5, v3, s46, -v5
	v_fmac_f32_e32 v5, 0x3377d1cf, v3
	v_fmac_f32_e32 v5, 0x3f317217, v3
	v_cmp_lt_f32_e64 s[16:17], |v3|, s39
	s_nop 1
	v_cndmask_b32_e64 v3, v3, v5, s[16:17]
	v_cndmask_b32_e32 v5, 0, v236, vcc
	v_sub_f32_e32 v3, v3, v5
	v_add_f32_e32 v2, v2, v3
	v_mul_f32_e64 v2, v2, -v42
	ds_write2st64_b32 v4, v2, v145 offset1:1
.LBB0_438:
	s_or_b64 exec, exec, s[64:65]
	s_barrier
	s_mov_b64 s[16:17], s[0:1]
	s_load_dwordx2 s[16:17], s[16:17], 0x48
	v_lshl_or_b32 v24, s59, 7, v114
	v_lshlrev_b32_e32 v42, 2, v24
	s_add_i32 s44, s9, s92
	s_cmp_gt_i32 s44, -1
	s_waitcnt lgkmcnt(0)
	global_load_dwordx2 v[2:3], v42, s[16:17]
	s_mov_b64 s[16:17], s[0:1]
	s_load_dwordx2 s[16:17], s[16:17], 0x48
	v_lshlrev_b32_e32 v10, 1, v24
	v_mov_b32_e32 v11, v43
	s_cselect_b64 s[64:65], -1, 0
	v_lshl_add_u64 v[10:11], s[18:19], 0, v[10:11]
	s_waitcnt lgkmcnt(0)
	v_lshl_add_u64 v[4:5], s[16:17], 0, v[42:43]
	v_add_co_u32_e32 v4, vcc, 0x3000, v4
	s_mov_b64 s[16:17], s[0:1]
	s_nop 0
	v_addc_co_u32_e32 v5, vcc, 0, v5, vcc
	global_load_dwordx2 v[4:5], v[4:5], off
	s_load_dwordx2 s[16:17], s[16:17], 0x48
	v_mov_b32_e32 v16, 0
	v_mov_b32_e32 v20, 0
	s_waitcnt lgkmcnt(0)
	v_lshl_add_u64 v[6:7], s[16:17], 0, v[42:43]
	v_add_co_u32_e32 v6, vcc, 0x6000, v6
	s_mov_b64 s[16:17], s[0:1]
	s_nop 0
	v_addc_co_u32_e32 v7, vcc, 0, v7, vcc
	global_load_dwordx2 v[6:7], v[6:7], off
	s_load_dwordx2 s[16:17], s[16:17], 0x48
	s_waitcnt lgkmcnt(0)
	v_lshl_add_u64 v[8:9], s[16:17], 0, v[42:43]
	v_add_co_u32_e32 v8, vcc, 0x9000, v8
	s_nop 1
	v_addc_co_u32_e32 v9, vcc, 0, v9, vcc
	global_load_dwordx2 v[8:9], v[8:9], off
	s_and_b64 vcc, exec, s[64:65]
	s_cbranch_vccz .LBB0_440
	s_add_u32 s16, s62, s44
	s_addc_u32 s17, s63, 0
	s_lshl_b64 s[16:17], s[16:17], 13
	v_lshl_add_u64 v[12:13], v[10:11], 0, s[16:17]
	global_load_dword v20, v[12:13], off
